# attention: 4 barriers per KV tile with waves 4-7 skewed one slot (explicit MFMA/softmax ping-pong), DMA issue moved into softmax-0 slot; + P10 batched epilogue
# speedup vs baseline: 1.0070x; 1.0070x over previous
.LBB0_1264:
	s_lshl_b32 s87, s35, 2
	s_xor_b64 s[16:17], s[44:45], -1
	s_add_i32 s87, s87, 4
	s_ashr_i32 s89, s86, 6
	s_movk_i32 s35, 0x110
	s_cmp_lt_u32 s85, 26
	v_mad_u32_u24 v229, v227, s35, v214
	s_cselect_b64 s[50:51], -1, 0
	s_lshl_b32 s35, s85, 10
	s_cmp_lt_u32 s6, 26
	s_cselect_b64 s[54:55], -1, 0
	s_lshl_b32 s44, s6, 10
	s_cmp_lt_u32 s7, 26
	s_cselect_b64 s[58:59], -1, 0
	s_lshl_b32 s45, s7, 10
	s_cmp_lt_u32 s14, 26
	s_cselect_b64 s[6:7], -1, 0
	s_lshl_b32 s46, s14, 10
	s_cmp_lt_u32 s15, 26
	s_cselect_b64 s[66:67], -1, 0
	s_lshl_b32 s47, s15, 10
	s_cmp_lt_u32 s33, 26
	s_cselect_b64 s[14:15], -1, 0
	s_lshl_b32 s33, s33, 10
	s_add_i32 s88, s35, 0
	s_add_i32 s90, s44, 0
	s_add_i32 s91, s45, 0
	s_add_i32 s92, s46, 0
	s_add_i32 s93, s47, 0
	s_add_i32 s94, s33, 0
	s_and_b64 s[44:45], s[50:51], exec
	s_cselect_b32 s33, s73, s37
	s_cselect_b32 s35, s74, s38
	s_cmp_lt_i32 s85, 26
	s_cselect_b64 s[44:45], -1, 0
	s_and_b64 s[46:47], s[48:49], exec
	s_cselect_b32 s47, s9, s35
	s_cselect_b32 s46, s8, s33
	s_and_b64 s[50:51], s[50:51], exec
	s_cselect_b32 s33, 13, 7
	s_and_b64 s[48:49], s[48:49], exec
	s_cselect_b32 s95, 18, s33
	s_and_b64 s[48:49], s[54:55], exec
	s_cselect_b32 s33, s73, s37
	s_cselect_b32 s35, s74, s38
	s_cmp_lt_i32 s85, 18
	s_cselect_b64 s[48:49], -1, 0
	s_and_b64 s[50:51], exec, s[52:53]
	s_cselect_b32 s51, s9, s35
	s_cselect_b32 s50, s8, s33
	s_and_b64 s[54:55], s[54:55], exec
	s_cselect_b32 s33, 13, 7
	s_and_b64 s[52:53], exec, s[52:53]
	s_cselect_b32 s96, 18, s33
	s_and_b64 s[52:53], s[58:59], exec
	s_cselect_b32 s33, s73, s37
	s_cselect_b32 s35, s74, s38
	s_cmp_lt_i32 s85, 10
	s_cselect_b64 s[52:53], -1, 0
	s_and_b64 s[54:55], exec, s[56:57]
	s_cselect_b32 s55, s9, s35
	s_cselect_b32 s54, s8, s33
	s_and_b64 s[58:59], s[58:59], exec
	s_cselect_b32 s33, 13, 7
	s_and_b64 s[56:57], exec, s[56:57]
	s_cselect_b32 s97, 18, s33
	s_and_b64 s[56:57], s[6:7], exec
	s_cselect_b32 s33, s73, s37
	s_cselect_b32 s35, s74, s38
	s_cmp_lt_i32 s85, 2
	s_cselect_b64 s[56:57], -1, 0
	s_and_b64 s[58:59], exec, s[60:61]
	s_cselect_b32 s59, s9, s35
	s_cselect_b32 s58, s8, s33
	s_and_b64 s[6:7], s[6:7], exec
	v_add_u32_e32 v230, 0, v229
	s_cselect_b32 s33, 13, 7
	s_and_b64 s[6:7], exec, s[60:61]
	s_waitcnt vmcnt(0)
	s_waitcnt vmcnt(0) lgkmcnt(0)
	s_barrier
	ds_read_b128 v[112:115], v1
	ds_read_b128 v[116:119], v1 offset:32
	ds_read_b128 v[120:123], v1 offset:64
	ds_read_b128 v[124:127], v1 offset:96
	ds_read_b128 v[168:171], v230
	ds_read_b128 v[160:163], v230 offset:32
	ds_read_b128 v[164:167], v230 offset:64
	ds_read_b128 v[152:155], v230 offset:96
	ds_read_b128 v[156:159], v230 offset:128
	ds_read_b128 v[128:131], v230 offset:160
	ds_read_b128 v[132:135], v230 offset:192
	ds_read_b128 v[136:139], v230 offset:224
	s_cselect_b32 s6, 18, s33
	s_and_b64 s[60:61], s[66:67], exec
	v_lshlrev_b32_e32 v1, 7, v227
	s_cselect_b32 s7, s73, s37
	s_cselect_b32 s33, s74, s38
	s_cmp_lt_i32 s85, -6
	v_sub_u32_e32 v1, v229, v1
	s_cselect_b64 s[60:61], -1, 0
	s_and_b64 s[62:63], exec, s[64:65]
	v_add_u32_e32 v231, 0, v1
	s_cselect_b32 s63, s9, s33
	s_cselect_b32 s62, s8, s7
	s_and_b64 s[66:67], s[66:67], exec
	ds_read_b128 v[140:143], v231 offset:17408
	ds_read_b128 v[144:147], v231 offset:17440
	ds_read_b128 v[148:151], v231 offset:17472
	ds_read_b128 v[208:211], v231 offset:17504
	s_cselect_b32 s7, 13, 7
	s_and_b64 s[64:65], exec, s[64:65]
	s_cselect_b32 s7, 18, s7
	s_and_b64 s[64:65], s[14:15], exec
	s_cselect_b32 s33, s73, s37
	s_cselect_b32 s35, s74, s38
	s_cmp_lt_i32 s85, -14
	s_cselect_b64 s[64:65], -1, 0
	s_and_b64 s[66:67], exec, s[68:69]
	v_mul_u32_u24_e32 v2, 0x90, v227
	s_cselect_b32 s67, s9, s35
	s_cselect_b32 s66, s8, s33
	s_and_b64 s[14:15], s[14:15], exec
	v_mov_b32_e32 v14, v215
	v_mov_b32_e32 v15, v215
	v_lshlrev_b32_e32 v232, 2, v0
	s_cselect_b32 s33, 13, 7
	s_and_b64 s[14:15], exec, s[68:69]
	v_add_u32_e32 v233, v2, v214
	v_mov_b32_e32 v0, v215
	v_mov_b32_e32 v1, v215
	v_mov_b32_e32 v2, v215
	v_mov_b32_e32 v3, v215
	v_mov_b32_e32 v4, v215
	v_mov_b32_e32 v5, v215
	v_mov_b32_e32 v6, v215
	v_mov_b32_e32 v7, v215
	v_mov_b32_e32 v8, v215
	v_mov_b32_e32 v9, v215
	v_mov_b32_e32 v10, v215
	v_mov_b32_e32 v11, v215
	v_mov_b32_e32 v12, v215
	v_mov_b32_e32 v13, v215
	v_mov_b64_e32 v[30:31], v[14:15]
	v_mov_b64_e32 v[46:47], v[14:15]
	v_mov_b64_e32 v[62:63], v[14:15]
	s_cselect_b32 s33, 18, s33
	v_add_u32_e32 v234, 0, v233
	s_add_i32 s14, s34, 0x100
	s_mov_b32 s15, 0
	v_mov_b32_e32 v235, 0
	v_mov_b32_e32 v236, 0xff800000
	v_mov_b64_e32 v[28:29], v[12:13]
	v_mov_b64_e32 v[26:27], v[10:11]
	v_mov_b64_e32 v[24:25], v[8:9]
	v_mov_b64_e32 v[22:23], v[6:7]
	v_mov_b64_e32 v[20:21], v[4:5]
	v_mov_b64_e32 v[18:19], v[2:3]
	v_mov_b64_e32 v[16:17], v[0:1]
	v_mov_b64_e32 v[44:45], v[12:13]
	v_mov_b64_e32 v[42:43], v[10:11]
	v_mov_b64_e32 v[40:41], v[8:9]
	v_mov_b64_e32 v[38:39], v[6:7]
	v_mov_b64_e32 v[36:37], v[4:5]
	v_mov_b64_e32 v[34:35], v[2:3]
	v_mov_b64_e32 v[32:33], v[0:1]
	v_mov_b64_e32 v[60:61], v[12:13]
	v_mov_b64_e32 v[58:59], v[10:11]
	v_mov_b64_e32 v[56:57], v[8:9]
	v_mov_b64_e32 v[54:55], v[6:7]
	v_mov_b64_e32 v[52:53], v[4:5]
	v_mov_b64_e32 v[50:51], v[2:3]
	v_mov_b64_e32 v[48:49], v[0:1]
	s_mov_b32 s35, 0
	s_cmp_ge_u32 s85, 4
	s_cbranch_scc0 .Lpp_x
	s_barrier
.Lpp_x:
.LBB0_1265:
	s_add_i32 s34, s35, 1
	s_cmp_ge_u32 s34, s87
	s_cselect_b64 s[68:69], -1, 0
.LBB0_1278:
	s_cmp_le_i32 s35, s89
	s_cselect_b64 s[70:71], -1, 0
	s_cmp_gt_i32 s35, s89
	s_cbranch_scc1 .LBB0_1288
	s_and_b32 vcc_lo, s35, 1
	s_mul_i32 vcc_hi, vcc_lo, 0x4800
	v_add_u32_e32 v237, vcc_hi, v234
	v_add_u32_e32 v238, 0xd000, v237
	s_mulk_i32 vcc_lo, 0x6800
	s_add_i32 vcc_lo, vcc_lo, 0
	s_setprio 1
	s_waitcnt lgkmcnt(0)
	v_mfma_f32_32x32x16_bf16 v[64:79], v[168:171], v[80:83], 0
	ds_read_b128 v[180:183], v237 offset:53248
	ds_read_b128 v[176:179], v237 offset:53280
	v_add_u32_e32 v172, vcc_lo, v229
	v_add_u32_e32 v239, vcc_lo, v233
	v_mfma_f32_32x32x16_bf16 v[64:79], v[160:163], v[84:87], v[64:79]
	ds_read_b128 v[196:199], v237 offset:57856
	ds_read_b128 v[188:191], v237 offset:62464
	v_mfma_f32_32x32x16_bf16 v[64:79], v[164:167], v[88:91], v[64:79]
	ds_read_b128 v[200:203], v238 offset:13824
	ds_read_b128 v[184:187], v238 offset:13856
	v_mfma_f32_32x32x16_bf16 v[64:79], v[152:155], v[92:95], v[64:79]
	ds_read_b128 v[204:207], v237 offset:57888
	ds_read_b128 v[192:195], v237 offset:62496
	v_mfma_f32_32x32x16_bf16 v[64:79], v[156:159], v[96:99], v[64:79]
	ds_read_b128 v[168:171], v172 offset:8704
	ds_read_b128 v[160:163], v172 offset:8736
	v_mfma_f32_32x32x16_bf16 v[64:79], v[128:131], v[100:103], v[64:79]
	ds_read_b128 v[164:167], v172 offset:8768
	ds_read_b128 v[152:155], v172 offset:8800
	v_mfma_f32_32x32x16_bf16 v[64:79], v[132:135], v[104:107], v[64:79]
	ds_read_b128 v[156:159], v172 offset:8832
	ds_read_b128 v[128:131], v172 offset:8864
	v_mfma_f32_32x32x16_bf16 v[64:79], v[136:139], v[108:111], v[64:79]
	ds_read_b128 v[132:135], v172 offset:8896
	ds_read_b128 v[136:139], v172 offset:8928
	v_mfma_f32_32x32x16_bf16 v[64:79], v[140:143], v[112:115], v[64:79]
	ds_read_b128 v[140:143], v239 offset:22016
	ds_read_b128 v[172:175], v239 offset:22112
	v_mfma_f32_32x32x16_bf16 v[64:79], v[144:147], v[116:119], v[64:79]
	ds_read_b128 v[144:147], v239 offset:22048
	v_mfma_f32_32x32x16_bf16 v[64:79], v[148:151], v[120:123], v[64:79]
	ds_read_b128 v[148:151], v239 offset:22080
	v_mfma_f32_32x32x16_bf16 v[64:79], v[208:211], v[124:127], v[64:79]
	s_setprio 0
	s_barrier
	s_and_b64 vcc, exec, s[68:69]
	s_cbranch_vccnz .Ldmq_end
	s_and_b32 s99, s34, 1
	s_mul_i32 s98, s99, 0x4800
	s_addk_i32 s98, 0x6800
	s_andn2_b64 vcc, exec, s[18:19]
	s_mulk_i32 s99, 0x6800
	s_cbranch_vccnz .Ldmq_1272
	s_and_b64 vcc, s[44:45], exec
	s_cselect_b32 vcc_lo, s99, s98
	s_lshl_b32 vcc_hi, s34, s95
	v_add_u32_e32 v253, vcc_hi, v221
	s_add_i32 m0, s88, vcc_lo
	s_nop 0
	global_load_lds_dwordx4 v253, s[46:47]
	s_andn2_b64 vcc, exec, s[20:21]
	s_cbranch_vccz .Ldmq_1273

.Ldmq_1269:
	s_and_b64 vcc, s[52:53], exec
	s_cselect_b32 vcc_lo, s99, s98
	s_lshl_b32 vcc_hi, s34, s97
	v_add_u32_e32 v253, vcc_hi, v223
	s_add_i32 m0, s91, vcc_lo
	s_nop 0
	global_load_lds_dwordx4 v253, s[54:55]
	s_andn2_b64 vcc, exec, s[24:25]
	s_cbranch_vccz .Ldmq_1275

.Ldmq_1271:
	s_and_b64 vcc, s[60:61], exec
	s_cselect_b32 vcc_lo, s99, s98
	s_lshl_b32 vcc_hi, s34, s7
	v_add_u32_e32 v253, vcc_hi, v225
	s_add_i32 m0, s93, vcc_lo
	s_nop 0
	global_load_lds_dwordx4 v253, s[62:63]
	s_andn2_b64 vcc, exec, s[42:43]
	s_cbranch_vccz .Ldmq_1277
	s_branch .Ldmq_end

.Ldmq_1273:
	s_and_b64 vcc, s[48:49], exec
	s_cselect_b32 vcc_lo, s99, s98
	s_lshl_b32 vcc_hi, s34, s96
	v_add_u32_e32 v253, vcc_hi, v222
	s_add_i32 m0, s90, vcc_lo
	s_nop 0
	global_load_lds_dwordx4 v253, s[50:51]
	s_andn2_b64 vcc, exec, s[22:23]
	s_cbranch_vccz .Ldmq_1269

.Ldmq_1275:
	s_and_b64 vcc, s[56:57], exec
	s_cselect_b32 vcc_lo, s99, s98
	s_lshl_b32 vcc_hi, s34, s6
	v_add_u32_e32 v253, vcc_hi, v224
	s_add_i32 m0, s92, vcc_lo
	s_nop 0
	global_load_lds_dwordx4 v253, s[58:59]
	s_andn2_b64 vcc, exec, s[30:31]
	s_cbranch_vccz .Ldmq_1271

.Ldmq_1277:
	s_and_b64 vcc, s[64:65], exec
	s_cselect_b32 s98, s99, s98
	s_lshl_b32 s99, s34, s33
	v_add_u32_e32 v253, s99, v226
	s_add_i32 m0, s94, s98
	s_nop 0
	global_load_lds_dwordx4 v253, s[66:67]
.Ldmq_end:
	s_add_i32 vcc_lo, s15, 31
	s_cmp_le_i32 vcc_lo, s86
	v_add_u32_e32 v208, s15, v232
	s_cbranch_scc1 .LBB0_1281
	v_cmp_lt_i32_e32 vcc, v208, v228
	v_add_u32_e32 v209, 2, v208
	s_nop 4
	v_cndmask_b32_e32 v65, v213, v65, vcc
	v_cmp_le_i32_e32 vcc, v208, v228
	s_nop 1
	v_cndmask_b32_e32 v64, v213, v64, vcc
	v_cmp_le_i32_e32 vcc, v209, v228
	v_add_u32_e32 v209, 3, v208
	s_nop 0
	v_cndmask_b32_e32 v66, v213, v66, vcc
	v_cmp_le_i32_e32 vcc, v209, v228
	v_add_u32_e32 v209, 8, v208
	s_nop 0
	v_cndmask_b32_e32 v67, v213, v67, vcc
	v_cmp_le_i32_e32 vcc, v209, v228
	v_add_u32_e32 v209, 9, v208
	s_nop 0
	v_cndmask_b32_e32 v68, v213, v68, vcc
	v_cmp_le_i32_e32 vcc, v209, v228
	v_add_u32_e32 v209, 10, v208
	s_nop 0
	v_cndmask_b32_e32 v69, v213, v69, vcc
	v_cmp_le_i32_e32 vcc, v209, v228
	v_add_u32_e32 v209, 11, v208
	s_nop 0
	v_cndmask_b32_e32 v70, v213, v70, vcc
	v_cmp_le_i32_e32 vcc, v209, v228
	v_add_u32_e32 v209, 16, v208
	s_nop 0
	v_cndmask_b32_e32 v71, v213, v71, vcc
	v_cmp_le_i32_e32 vcc, v209, v228
	v_add_u32_e32 v209, 17, v208
	s_nop 0
	v_cndmask_b32_e32 v72, v213, v72, vcc
	v_cmp_le_i32_e32 vcc, v209, v228
	v_add_u32_e32 v209, 18, v208
	s_nop 0
	v_cndmask_b32_e32 v73, v213, v73, vcc
	v_cmp_le_i32_e32 vcc, v209, v228
	v_add_u32_e32 v209, 19, v208
	s_nop 0
	v_cndmask_b32_e32 v74, v213, v74, vcc
	v_cmp_le_i32_e32 vcc, v209, v228
	v_add_u32_e32 v209, 24, v208
	s_nop 0
	v_cndmask_b32_e32 v75, v213, v75, vcc
	v_cmp_le_i32_e32 vcc, v209, v228
	v_add_u32_e32 v209, 25, v208
	s_nop 0
	v_cndmask_b32_e32 v76, v213, v76, vcc
	v_cmp_le_i32_e32 vcc, v209, v228
	v_add_u32_e32 v209, 26, v208
	s_nop 0
	v_cndmask_b32_e32 v77, v213, v77, vcc
	v_cmp_le_i32_e32 vcc, v209, v228
	v_add_u32_e32 v209, 27, v208
	s_nop 0
	v_cndmask_b32_e32 v78, v213, v78, vcc
	v_cmp_le_i32_e32 vcc, v209, v228
	s_nop 1
	v_cndmask_b32_e32 v79, v213, v79, vcc

.LBB0_1283:
	v_sub_f32_e32 v64, v64, v236
	v_exp_f32_e32 v209, v64
	v_sub_f32_e32 v64, v65, v236
	v_exp_f32_e32 v210, v64
	v_sub_f32_e32 v64, v66, v236
	v_exp_f32_e32 v211, v64
	v_sub_f32_e32 v64, v67, v236
	v_exp_f32_e32 v239, v64
	v_sub_f32_e32 v64, v68, v236
	v_exp_f32_e32 v240, v64
	v_sub_f32_e32 v64, v69, v236
	v_exp_f32_e32 v241, v64
	v_sub_f32_e32 v64, v70, v236
	v_exp_f32_e32 v242, v64
	v_sub_f32_e32 v64, v71, v236
	v_exp_f32_e32 v243, v64
	v_sub_f32_e32 v64, v72, v236
	v_exp_f32_e32 v244, v64
	v_sub_f32_e32 v64, v73, v236
	v_exp_f32_e32 v245, v64
	v_sub_f32_e32 v64, v74, v236
	v_exp_f32_e32 v246, v64
	v_sub_f32_e32 v64, v75, v236
	v_exp_f32_e32 v247, v64
	v_sub_f32_e32 v64, v76, v236
	v_exp_f32_e32 v248, v64
	v_sub_f32_e32 v64, v77, v236
	v_exp_f32_e32 v249, v64
	v_sub_f32_e32 v64, v78, v236
	v_exp_f32_e32 v250, v64
	v_sub_f32_e32 v64, v79, v236
	v_exp_f32_e32 v251, v64
	v_cvt_pk_bf16_f32 v64, v209, v210
	v_cvt_pk_bf16_f32 v65, v211, v239
	v_cvt_pk_bf16_f32 v66, v240, v241
	v_cvt_pk_bf16_f32 v67, v242, v243
	v_cvt_pk_bf16_f32 v68, v244, v245
	v_cvt_pk_bf16_f32 v69, v246, v247
	v_cvt_pk_bf16_f32 v70, v248, v249
	v_cvt_pk_bf16_f32 v71, v250, v251
	s_barrier
	s_setprio 1
	s_waitcnt lgkmcnt(0)
	v_mfma_f32_32x32x16_bf16 v[48:63], v[180:183], v[64:67], v[48:63]
	v_mfma_f32_32x32x16_bf16 v[32:47], v[196:199], v[64:67], v[32:47]
	v_mfma_f32_32x32x16_bf16 v[16:31], v[188:191], v[64:67], v[16:31]
	v_mfma_f32_32x32x16_bf16 v[0:15], v[200:203], v[64:67], v[0:15]
	v_mfma_f32_32x32x16_bf16 v[48:63], v[176:179], v[68:71], v[48:63]
	v_mfma_f32_32x32x16_bf16 v[32:47], v[204:207], v[68:71], v[32:47]
	v_mfma_f32_32x32x16_bf16 v[16:31], v[192:195], v[68:71], v[16:31]
	v_mfma_f32_32x32x16_bf16 v[0:15], v[184:187], v[68:71], v[0:15]
	s_setprio 0
	s_setprio 1
	v_mfma_f32_32x32x16_bf16 v[64:79], v[168:171], v[80:83], 0
	ds_read_b128 v[180:183], v237 offset:53312
	v_mfma_f32_32x32x16_bf16 v[64:79], v[160:163], v[84:87], v[64:79]
	ds_read_b128 v[176:179], v237 offset:53344
	v_mfma_f32_32x32x16_bf16 v[64:79], v[164:167], v[88:91], v[64:79]
	ds_read_b128 v[184:187], v237 offset:57920
	v_mfma_f32_32x32x16_bf16 v[64:79], v[152:155], v[92:95], v[64:79]
	ds_read_b128 v[192:195], v237 offset:62528
	v_mfma_f32_32x32x16_bf16 v[64:79], v[156:159], v[96:99], v[64:79]
	ds_read_b128 v[196:199], v238 offset:13888
	v_mfma_f32_32x32x16_bf16 v[64:79], v[128:131], v[100:103], v[64:79]
	ds_read_b128 v[188:191], v238 offset:13920
	v_mfma_f32_32x32x16_bf16 v[64:79], v[132:135], v[104:107], v[64:79]
	ds_read_b128 v[200:203], v237 offset:57952
	v_mfma_f32_32x32x16_bf16 v[64:79], v[136:139], v[108:111], v[64:79]
	ds_read_b128 v[204:207], v237 offset:62560
	v_mfma_f32_32x32x16_bf16 v[64:79], v[140:143], v[112:115], v[64:79]
	v_mfma_f32_32x32x16_bf16 v[64:79], v[144:147], v[116:119], v[64:79]
	v_mfma_f32_32x32x16_bf16 v[64:79], v[148:151], v[120:123], v[64:79]
	v_mfma_f32_32x32x16_bf16 v[64:79], v[172:175], v[124:127], v[64:79]
	s_setprio 0
	s_waitcnt vmcnt(0) lgkmcnt(0)
	s_barrier
	s_add_i32 vcc_lo, s15, 63
	s_cmp_le_i32 vcc_lo, s86
	s_cbranch_scc1 .LBB0_1285
	v_add_u32_e32 v237, 32, v208
	v_cmp_lt_i32_e32 vcc, v237, v228
	s_nop 5
	v_cndmask_b32_e32 v65, v213, v65, vcc
	v_cmp_le_i32_e32 vcc, v237, v228
	v_add_u32_e32 v237, 34, v208
	s_nop 0
	v_cndmask_b32_e32 v64, v213, v64, vcc
	v_cmp_le_i32_e32 vcc, v237, v228
	v_add_u32_e32 v237, 35, v208
	s_nop 0
	v_cndmask_b32_e32 v66, v213, v66, vcc
	v_cmp_le_i32_e32 vcc, v237, v228
	v_add_u32_e32 v237, 40, v208
	s_nop 0
	v_cndmask_b32_e32 v67, v213, v67, vcc
	v_cmp_le_i32_e32 vcc, v237, v228
	v_add_u32_e32 v237, 41, v208
	s_nop 0
	v_cndmask_b32_e32 v68, v213, v68, vcc
	v_cmp_le_i32_e32 vcc, v237, v228
	v_add_u32_e32 v237, 42, v208
	s_nop 0
	v_cndmask_b32_e32 v69, v213, v69, vcc
	v_cmp_le_i32_e32 vcc, v237, v228
	v_add_u32_e32 v237, 43, v208
	s_nop 0
	v_cndmask_b32_e32 v70, v213, v70, vcc
	v_cmp_le_i32_e32 vcc, v237, v228
	v_add_u32_e32 v237, 48, v208
	s_nop 0
	v_cndmask_b32_e32 v71, v213, v71, vcc
	v_cmp_le_i32_e32 vcc, v237, v228
	v_add_u32_e32 v237, 49, v208
	s_nop 0
	v_cndmask_b32_e32 v72, v213, v72, vcc
	v_cmp_le_i32_e32 vcc, v237, v228
	v_add_u32_e32 v237, 50, v208
	s_nop 0
	v_cndmask_b32_e32 v73, v213, v73, vcc
	v_cmp_le_i32_e32 vcc, v237, v228
	v_add_u32_e32 v237, 51, v208
	s_nop 0
	v_cndmask_b32_e32 v74, v213, v74, vcc
	v_cmp_le_i32_e32 vcc, v237, v228
	v_add_u32_e32 v237, 56, v208
	s_nop 0
	v_cndmask_b32_e32 v75, v213, v75, vcc
	v_cmp_le_i32_e32 vcc, v237, v228
	v_add_u32_e32 v237, 57, v208
	s_nop 0
	v_cndmask_b32_e32 v76, v213, v76, vcc
	v_cmp_le_i32_e32 vcc, v237, v228
	v_add_u32_e32 v237, 58, v208
	v_add_u32_e32 v208, 59, v208
	v_cndmask_b32_e32 v77, v213, v77, vcc
	v_cmp_le_i32_e32 vcc, v237, v228
	s_nop 1
	v_cndmask_b32_e32 v78, v213, v78, vcc
	v_cmp_le_i32_e32 vcc, v208, v228
	s_nop 1
	v_cndmask_b32_e32 v79, v213, v79, vcc

.LBB0_1288:
	s_barrier
	s_and_b64 vcc, exec, s[68:69]
	s_cbranch_vccnz .Ldmr_end
	s_and_b32 s99, s34, 1
	s_mul_i32 s98, s99, 0x4800
	s_addk_i32 s98, 0x6800
	s_andn2_b64 vcc, exec, s[18:19]
	s_mulk_i32 s99, 0x6800
	s_cbranch_vccnz .Ldmr_1272
	s_and_b64 vcc, s[44:45], exec
	s_cselect_b32 vcc_lo, s99, s98
	s_lshl_b32 vcc_hi, s34, s95
	v_add_u32_e32 v253, vcc_hi, v221
	s_add_i32 m0, s88, vcc_lo
	s_nop 0
	global_load_lds_dwordx4 v253, s[46:47]
	s_andn2_b64 vcc, exec, s[20:21]
	s_cbranch_vccz .Ldmr_1273

.Ldmr_end:
	s_barrier
	s_waitcnt vmcnt(0)
	s_barrier
	s_waitcnt lgkmcnt(0)
	v_mov_b64_e32 v[172:173], v[208:209]
	v_mov_b64_e32 v[174:175], v[210:211]

.Lpp_exit:
	s_cmp_ge_u32 s85, 4
	s_cbranch_scc1 .LBB0_1179
	s_barrier
	s_branch .LBB0_1179

	.amdhsa_kernel _Z8mega_fwd6Params
		.amdhsa_group_segment_fixed_size 0
		.amdhsa_private_segment_fixed_size 0
		.amdhsa_kernarg_size 728
		.amdhsa_user_sgpr_count 2
		.amdhsa_user_sgpr_dispatch_ptr 0
		.amdhsa_user_sgpr_queue_ptr 0
		.amdhsa_user_sgpr_kernarg_segment_ptr 1
		.amdhsa_user_sgpr_dispatch_id 0
		.amdhsa_user_sgpr_kernarg_preload_length 0
		.amdhsa_user_sgpr_kernarg_preload_offset 0
		.amdhsa_user_sgpr_private_segment_size 0
		.amdhsa_uses_dynamic_stack 0
		.amdhsa_enable_private_segment 0
		.amdhsa_system_sgpr_workgroup_id_x 1
		.amdhsa_system_sgpr_workgroup_id_y 0
		.amdhsa_system_sgpr_workgroup_id_z 0
		.amdhsa_system_sgpr_workgroup_info 0
		.amdhsa_system_vgpr_workitem_id 2
		.amdhsa_next_free_vgpr 255
		.amdhsa_next_free_sgpr 102
		.amdhsa_accum_offset 256
		.amdhsa_reserve_vcc 1
		.amdhsa_float_round_mode_32 0
		.amdhsa_float_round_mode_16_64 0
		.amdhsa_float_denorm_mode_32 3
		.amdhsa_float_denorm_mode_16_64 3
		.amdhsa_dx10_clamp 1
		.amdhsa_ieee_mode 1
		.amdhsa_fp16_overflow 0
		.amdhsa_tg_split 0
		.amdhsa_exception_fp_ieee_invalid_op 0
		.amdhsa_exception_fp_denorm_src 0
		.amdhsa_exception_fp_ieee_div_zero 0
		.amdhsa_exception_fp_ieee_overflow 0
		.amdhsa_exception_fp_ieee_underflow 0
		.amdhsa_exception_fp_ieee_inexact 0
		.amdhsa_exception_int_div_zero 0
	.end_amdhsa_kernel

amdhsa.kernels:
  - .agpr_count:     0
    .args:
      - .offset:         0
        .size:           472
        .value_kind:     by_value
      - .offset:         472
        .size:           4
        .value_kind:     hidden_block_count_x
      - .offset:         476
        .size:           4
        .value_kind:     hidden_block_count_y
      - .offset:         480
        .size:           4
        .value_kind:     hidden_block_count_z
      - .offset:         484
        .size:           2
        .value_kind:     hidden_group_size_x
      - .offset:         486
        .size:           2
        .value_kind:     hidden_group_size_y
      - .offset:         488
        .size:           2
        .value_kind:     hidden_group_size_z
      - .offset:         490
        .size:           2
        .value_kind:     hidden_remainder_x
      - .offset:         492
        .size:           2
        .value_kind:     hidden_remainder_y
      - .offset:         494
        .size:           2
        .value_kind:     hidden_remainder_z
      - .offset:         512
        .size:           8
        .value_kind:     hidden_global_offset_x
      - .offset:         520
        .size:           8
        .value_kind:     hidden_global_offset_y
      - .offset:         528
        .size:           8
        .value_kind:     hidden_global_offset_z
      - .offset:         536
        .size:           2
        .value_kind:     hidden_grid_dims
      - .offset:         560
        .size:           8
        .value_kind:     hidden_multigrid_sync_arg
      - .offset:         592
        .size:           4
        .value_kind:     hidden_dynamic_lds_size
    .group_segment_fixed_size: 0
    .kernarg_segment_align: 8
    .kernarg_segment_size: 728
    .language:       OpenCL C
    .language_version:
      - 2
      - 0
    .max_flat_workgroup_size: 512
    .name:           _Z8mega_fwd6Params
    .private_segment_fixed_size: 0
    .sgpr_count:     108
    .sgpr_spill_count: 22
    .symbol:         _Z8mega_fwd6Params.kd
    .uniform_work_group_size: 1
    .uses_dynamic_stack: false
    .vgpr_count:     255
    .vgpr_spill_count: 0
    .wavefront_size: 64
